# v15 + unit-stride radix-4 levels (forward level 0 and inverse level 0 with spectrum product) rewritten by hand, khat loads still 3 iterations ahead
# speedup vs baseline: 1.0055x; 1.0055x over previous
; DI float2 twid(float r) { return float2{__builtin_amdgcn_cosf(r), -__builtin_amdgcn_sinf(r)}; }
; DI void bfly_fwd(float2 a0, float2 a1, float2 a2, float2 a3, float r, float2& o0, float2& o1, float2& o2, float2& o3) {
;   float2 t0 = {a0.x + a2.x, a0.y + a2.y}, t1 = {a0.x - a2.x, a0.y - a2.y}, t2 = {a1.x + a3.x, a1.y + a3.y}, t3 = {a1.x - a3.x, a1.y - a3.y};
;   float2 b0 = {t0.x + t2.x, t0.y + t2.y}, b2 = {t0.x - t2.x, t0.y - t2.y}, b1 = {t1.x + t3.y, t1.y - t3.x}, b3 = {t1.x - t3.y, t1.y + t3.x};
;   float2 w1 = twid(r), w2 = cmul(w1, w1), w3 = cmul(w2, w1);
;   o0 = b0; o1 = cmul(b1, w1); o2 = cmul(b2, w2); o3 = cmul(b3, w3);
; }
;   const int Q = 1 << lq; const float invM = 1.f / (float)(4 << lq);
;   for (int bb = tid; bb < NBT * (N / 4); bb += NTHR) { const int b = bb & (N / 4 - 1); float2* z = z0 + (bb / (N / 4)) * N; int j = b & (Q - 1), base = ((b >> lq) << (lq + 2)) + j; float2 o0, o1, o2, o3;
;     bfly_fwd(z[base], z[base + Q], z[base + 2 * Q], z[base + 3 * Q], (float)j * invM, o0, o1, o2, o3);
;     z[base] = o0; z[base + Q] = o1; z[base + 2 * Q] = o2; z[base + 3 * Q] = o3; }
;   __syncthreads();
; }
.LBB0_1499:
	v_ashrrev_i32_e32 v13, 31, v12
	v_lshrrev_b32_e32 v13, 21, v13
	v_add_lshl_u32 v13, v12, v13, 5
	v_and_b32_e32 v14, 0x1ffc, v11
	v_and_b32_e32 v13, 0xffff0000, v13
	v_lshlrev_b32_e32 v14, 3, v14
	v_add3_u32 v13, 16, v13, v14
	ds_read_b128 v[14:17], v13
	ds_read_b128 v[18:21], v13 offset:16
	v_cmp_lt_i32_e32 vcc, s3, v12
	v_add_u32_e32 v11, 0x800, v11
	s_or_b64 s[8:9], vcc, s[8:9]
	s_waitcnt lgkmcnt(0)
	v_pk_add_f32 v[22:23], v[14:15], v[18:19]
	v_pk_add_f32 v[26:27], v[16:17], v[20:21]
	v_pk_add_f32 v[24:25], v[14:15], v[18:19] neg_lo:[0,1] neg_hi:[0,1]
	v_pk_add_f32 v[28:29], v[16:17], v[20:21] neg_lo:[0,1] neg_hi:[0,1]
	v_pk_add_f32 v[14:15], v[22:23], v[26:27]
	v_pk_add_f32 v[18:19], v[22:23], v[26:27] neg_lo:[0,1] neg_hi:[0,1]
	v_pk_add_f32 v[16:17], v[24:25], v[28:29] op_sel:[0,1] op_sel_hi:[1,0] neg_hi:[0,1]
	v_pk_add_f32 v[20:21], v[24:25], v[28:29] op_sel:[0,1] op_sel_hi:[1,0] neg_lo:[0,1]
	s_nop 0
	ds_write_b128 v13, v[14:17]
	ds_write_b128 v13, v[18:21] offset:16
	v_add_u32_e32 v13, 0x200, v12
	v_mov_b32_e32 v12, v13
	s_andn2_b64 exec, exec, s[8:9]
	s_cbranch_execnz .LBB0_1499

; DI float2 twid(float r) { return float2{__builtin_amdgcn_cosf(r), -__builtin_amdgcn_sinf(r)}; }
; DI void bfly_fwd(float2 a0, float2 a1, float2 a2, float2 a3, float r, float2& o0, float2& o1, float2& o2, float2& o3) {
;   float2 t0 = {a0.x + a2.x, a0.y + a2.y}, t1 = {a0.x - a2.x, a0.y - a2.y}, t2 = {a1.x + a3.x, a1.y + a3.y}, t3 = {a1.x - a3.x, a1.y - a3.y};
;   float2 b0 = {t0.x + t2.x, t0.y + t2.y}, b2 = {t0.x - t2.x, t0.y - t2.y}, b1 = {t1.x + t3.y, t1.y - t3.x}, b3 = {t1.x - t3.y, t1.y + t3.x};
;   float2 w1 = twid(r), w2 = cmul(w1, w1), w3 = cmul(w2, w1);
;   o0 = b0; o1 = cmul(b1, w1); o2 = cmul(b2, w2); o3 = cmul(b3, w3);
; }
;   const int Q = 1 << lq; const float invM = 1.f / (float)(4 << lq);
;   for (int bb = tid; bb < NBT * (N / 4); bb += NTHR) { const int b = bb & (N / 4 - 1); float2* z = z0 + (bb / (N / 4)) * N; int j = b & (Q - 1), base = ((b >> lq) << (lq + 2)) + j; float2 o0, o1, o2, o3;
;     bfly_fwd(z[base], z[base + Q], z[base + 2 * Q], z[base + 3 * Q], (float)j * invM, o0, o1, o2, o3);
;     z[base] = o0; z[base + Q] = o1; z[base + 2 * Q] = o2; z[base + 3 * Q] = o3; }
;   __syncthreads();
; }
.LBB0_1527:
	v_ashrrev_i32_e32 v13, 31, v12
	v_lshrrev_b32_e32 v13, 20, v13
	v_add_lshl_u32 v13, v12, v13, 5
	v_and_b32_e32 v14, 0x3ffc, v11
	v_and_b32_e32 v13, 0xfffe0000, v13
	v_lshlrev_b32_e32 v14, 3, v14
	v_add3_u32 v13, 16, v13, v14
	ds_read_b128 v[14:17], v13
	ds_read_b128 v[18:21], v13 offset:16
	v_cmp_lt_i32_e32 vcc, s25, v12
	v_add_u32_e32 v11, 0x800, v11
	s_or_b64 s[8:9], vcc, s[8:9]
	s_waitcnt lgkmcnt(0)
	v_pk_add_f32 v[22:23], v[14:15], v[18:19]
	v_pk_add_f32 v[26:27], v[16:17], v[20:21]
	v_pk_add_f32 v[24:25], v[14:15], v[18:19] neg_lo:[0,1] neg_hi:[0,1]
	v_pk_add_f32 v[28:29], v[16:17], v[20:21] neg_lo:[0,1] neg_hi:[0,1]
	v_pk_add_f32 v[14:15], v[22:23], v[26:27]
	v_pk_add_f32 v[18:19], v[22:23], v[26:27] neg_lo:[0,1] neg_hi:[0,1]
	v_pk_add_f32 v[16:17], v[24:25], v[28:29] op_sel:[0,1] op_sel_hi:[1,0] neg_hi:[0,1]
	v_pk_add_f32 v[20:21], v[24:25], v[28:29] op_sel:[0,1] op_sel_hi:[1,0] neg_lo:[0,1]
	s_nop 0
	ds_write_b128 v13, v[14:17]
	ds_write_b128 v13, v[18:21] offset:16
	v_add_u32_e32 v13, 0x200, v12
	v_mov_b32_e32 v12, v13
	s_andn2_b64 exec, exec, s[8:9]
	s_cbranch_execnz .LBB0_1527

; DI float2 twid(float r) { return float2{__builtin_amdgcn_cosf(r), -__builtin_amdgcn_sinf(r)}; }
; DI void bfly_fwd(float2 a0, float2 a1, float2 a2, float2 a3, float r, float2& o0, float2& o1, float2& o2, float2& o3) {
;   float2 t0 = {a0.x + a2.x, a0.y + a2.y}, t1 = {a0.x - a2.x, a0.y - a2.y}, t2 = {a1.x + a3.x, a1.y + a3.y}, t3 = {a1.x - a3.x, a1.y - a3.y};
;   float2 b0 = {t0.x + t2.x, t0.y + t2.y}, b2 = {t0.x - t2.x, t0.y - t2.y}, b1 = {t1.x + t3.y, t1.y - t3.x}, b3 = {t1.x - t3.y, t1.y + t3.x};
;   float2 w1 = twid(r), w2 = cmul(w1, w1), w3 = cmul(w2, w1);
;   o0 = b0; o1 = cmul(b1, w1); o2 = cmul(b2, w2); o3 = cmul(b3, w3);
; }
;   const int Q = 1 << lq; const float invM = 1.f / (float)(4 << lq);
;   for (int bb = tid; bb < NBT * (N / 4); bb += NTHR) { const int b = bb & (N / 4 - 1); float2* z = z0 + (bb / (N / 4)) * N; int j = b & (Q - 1), base = ((b >> lq) << (lq + 2)) + j; float2 o0, o1, o2, o3;
;     bfly_fwd(z[base], z[base + Q], z[base + 2 * Q], z[base + 3 * Q], (float)j * invM, o0, o1, o2, o3);
;     z[base] = o0; z[base + Q] = o1; z[base + 2 * Q] = o2; z[base + 3 * Q] = o3; }
;   __syncthreads();
; }
.LBB0_1609:
	v_ashrrev_i32_e32 v4, 31, v3
	v_lshrrev_b32_e32 v4, 21, v4
	v_add_lshl_u32 v4, v3, v4, 5
	v_and_b32_e32 v5, 0x1ffc, v2
	v_and_b32_e32 v4, 0xffff0000, v4
	v_lshlrev_b32_e32 v5, 3, v5
	v_add3_u32 v17, 16, v4, v5
	ds_read_b128 v[4:7], v17
	ds_read_b128 v[8:11], v17 offset:16
	v_cmp_lt_i32_e64 s[12:13], s25, v3
	v_add_u32_e32 v2, 0x800, v2
	s_or_b64 s[80:81], s[12:13], s[80:81]
	s_waitcnt lgkmcnt(0)
	v_pk_add_f32 v[12:13], v[4:5], v[8:9]
	v_pk_add_f32 v[20:21], v[6:7], v[10:11]
	v_pk_add_f32 v[18:19], v[4:5], v[8:9] neg_lo:[0,1] neg_hi:[0,1]
	v_pk_add_f32 v[22:23], v[6:7], v[10:11] neg_lo:[0,1] neg_hi:[0,1]
	v_pk_add_f32 v[4:5], v[12:13], v[20:21]
	v_pk_add_f32 v[8:9], v[12:13], v[20:21] neg_lo:[0,1] neg_hi:[0,1]
	v_pk_add_f32 v[6:7], v[18:19], v[22:23] op_sel:[0,1] op_sel_hi:[1,0] neg_hi:[0,1]
	v_pk_add_f32 v[10:11], v[18:19], v[22:23] op_sel:[0,1] op_sel_hi:[1,0] neg_lo:[0,1]
	s_nop 0
	ds_write_b128 v17, v[4:7]
	ds_write_b128 v17, v[8:11] offset:16
	v_add_u32_e32 v4, 0x200, v3
	v_mov_b32_e32 v3, v4
	s_andn2_b64 exec, exec, s[80:81]
	s_cbranch_execnz .LBB0_1609

; DI float2 twid(float r) { return float2{__builtin_amdgcn_cosf(r), -__builtin_amdgcn_sinf(r)}; }
; DI void bfly_inv(float2 s0, float2 s1, float2 s2, float2 s3, float r, float2& o0, float2& o1, float2& o2, float2& o3) {
;   float2 w1 = twid(r), w2 = cmul(w1, w1), w3 = cmul(w2, w1);
;   float2 c0 = s0, c1 = cmulc(s1, w1), c2 = cmulc(s2, w2), c3 = cmulc(s3, w3);
;   float2 t0 = {c0.x + c2.x, c0.y + c2.y}, t1 = {c0.x - c2.x, c0.y - c2.y}, t2 = {c1.x + c3.x, c1.y + c3.y}, t3 = {c1.x - c3.x, c1.y - c3.y};
;   o0 = float2{t0.x + t2.x, t0.y + t2.y}; o2 = float2{t0.x - t2.x, t0.y - t2.y}; o1 = float2{t1.x - t3.y, t1.y + t3.x}; o3 = float2{t1.x + t3.y, t1.y - t3.x};
; }
;   for (int bb = tid; bb < NBT * (N / 4); bb += NTHR) { const int b = bb & (N / 4 - 1); float2* z = z0 + (bb / (N / 4)) * N; const int base = b * 4; f32x4 k01 = *(const f32x4*)(kh + base), k23 = *(const f32x4*)(kh + base + 2); float2 o0, o1, o2, o3;
;     bfly_inv(cmul(z[base], float2{k01[0], k01[1]}), cmul(z[base + 1], float2{k01[2], k01[3]}), cmul(z[base + 2], float2{k23[0], k23[1]}), cmul(z[base + 3], float2{k23[2], k23[3]}), 0.f, o0, o1, o2, o3);
;     z[base] = o0; z[base + 1] = o1; z[base + 2] = o2; z[base + 3] = o3; }
;   __syncthreads();
.LBB0_1612:
	v_mov_b32_e32 v218, v2
	v_lshlrev_b32_e32 v219, 3, v218
	v_and_b32_e32 v220, 0xffe0, v219
	global_load_dwordx4 v[222:225], v220, s[80:81] offset:16
	global_load_dwordx4 v[226:229], v220, s[80:81]
	v_add_u32_e32 v218, 0x800, v218
	v_lshlrev_b32_e32 v219, 3, v218
	v_and_b32_e32 v220, 0xffe0, v219
	global_load_dwordx4 v[230:233], v220, s[80:81] offset:16
	global_load_dwordx4 v[234:237], v220, s[80:81]
	v_add_u32_e32 v218, 0x800, v218
	v_lshlrev_b32_e32 v219, 3, v218
	v_and_b32_e32 v220, 0xffe0, v219
	global_load_dwordx4 v[242:245], v220, s[80:81] offset:16
	global_load_dwordx4 v[246:249], v220, s[80:81]
	v_add_u32_e32 v218, 0x800, v218
	v_ashrrev_i32_e32 v4, 31, v3
	v_lshrrev_b32_e32 v4, 21, v4
	v_add_lshl_u32 v4, v3, v4, 5
	v_and_b32_e32 v12, 0xffff0000, v4
	v_lshlrev_b32_e32 v4, 3, v2
	v_and_b32_e32 v13, 0xffe0, v4
	s_nop 0
	v_add3_u32 v17, 16, v12, v13
	ds_read_b128 v[18:21], v17
	ds_read_b128 v[22:25], v17 offset:16
	s_nop 0
	v_add_u32_e32 v2, 0x800, v2
	s_nop 0
	s_waitcnt vmcnt(4) lgkmcnt(0)
	v_pk_mul_f32 v[214:215], v[18:19], v[226:227] op_sel:[1,1] op_sel_hi:[1,0]
	v_pk_mul_f32 v[216:217], v[20:21], v[228:229] op_sel:[1,1] op_sel_hi:[1,0]
	v_pk_fma_f32 v[18:19], v[18:19], v[226:227], v[214:215] op_sel_hi:[0,1,1] neg_lo:[0,0,1]
	v_pk_fma_f32 v[20:21], v[20:21], v[228:229], v[216:217] op_sel_hi:[0,1,1] neg_lo:[0,0,1]
	v_pk_mul_f32 v[214:215], v[22:23], v[222:223] op_sel:[1,1] op_sel_hi:[1,0]
	v_pk_mul_f32 v[216:217], v[24:25], v[224:225] op_sel:[1,1] op_sel_hi:[1,0]
	v_pk_fma_f32 v[22:23], v[22:23], v[222:223], v[214:215] op_sel_hi:[0,1,1] neg_lo:[0,0,1]
	v_pk_fma_f32 v[24:25], v[24:25], v[224:225], v[216:217] op_sel_hi:[0,1,1] neg_lo:[0,0,1]
	v_pk_add_f32 v[26:27], v[18:19], v[22:23]
	v_pk_add_f32 v[190:191], v[20:21], v[24:25]
	v_pk_add_f32 v[188:189], v[18:19], v[22:23] neg_lo:[0,1] neg_hi:[0,1]
	v_pk_add_f32 v[192:193], v[20:21], v[24:25] neg_lo:[0,1] neg_hi:[0,1]
	v_pk_add_f32 v[18:19], v[26:27], v[190:191]
	v_pk_add_f32 v[22:23], v[26:27], v[190:191] neg_lo:[0,1] neg_hi:[0,1]
	v_pk_add_f32 v[20:21], v[188:189], v[192:193] op_sel:[0,1] op_sel_hi:[1,0] neg_lo:[0,1]
	v_pk_add_f32 v[24:25], v[188:189], v[192:193] op_sel:[0,1] op_sel_hi:[1,0] neg_hi:[0,1]
	s_nop 0
	ds_write_b128 v17, v[18:21]
	ds_write_b128 v17, v[22:25] offset:16
	v_add_u32_e32 v222, 0x200, v3
	v_mov_b32_e32 v3, v222
	s_nop 0
	v_lshlrev_b32_e32 v219, 3, v218
	v_and_b32_e32 v220, 0xffe0, v219
	global_load_dwordx4 v[222:225], v220, s[80:81] offset:16
	global_load_dwordx4 v[226:229], v220, s[80:81]
	v_add_u32_e32 v218, 0x800, v218
	v_ashrrev_i32_e32 v4, 31, v3
	v_lshrrev_b32_e32 v4, 21, v4
	v_add_lshl_u32 v4, v3, v4, 5
	v_and_b32_e32 v12, 0xffff0000, v4
	v_lshlrev_b32_e32 v4, 3, v2
	v_and_b32_e32 v13, 0xffe0, v4
	s_nop 0
	v_add3_u32 v17, 16, v12, v13
	ds_read_b128 v[18:21], v17
	ds_read_b128 v[22:25], v17 offset:16
	s_nop 0
	v_add_u32_e32 v2, 0x800, v2
	s_nop 0
	s_waitcnt vmcnt(4) lgkmcnt(0)
	v_pk_mul_f32 v[214:215], v[18:19], v[234:235] op_sel:[1,1] op_sel_hi:[1,0]
	v_pk_mul_f32 v[216:217], v[20:21], v[236:237] op_sel:[1,1] op_sel_hi:[1,0]
	v_pk_fma_f32 v[18:19], v[18:19], v[234:235], v[214:215] op_sel_hi:[0,1,1] neg_lo:[0,0,1]
	v_pk_fma_f32 v[20:21], v[20:21], v[236:237], v[216:217] op_sel_hi:[0,1,1] neg_lo:[0,0,1]
	v_pk_mul_f32 v[214:215], v[22:23], v[230:231] op_sel:[1,1] op_sel_hi:[1,0]
	v_pk_mul_f32 v[216:217], v[24:25], v[232:233] op_sel:[1,1] op_sel_hi:[1,0]
	v_pk_fma_f32 v[22:23], v[22:23], v[230:231], v[214:215] op_sel_hi:[0,1,1] neg_lo:[0,0,1]
	v_pk_fma_f32 v[24:25], v[24:25], v[232:233], v[216:217] op_sel_hi:[0,1,1] neg_lo:[0,0,1]
	v_pk_add_f32 v[26:27], v[18:19], v[22:23]
	v_pk_add_f32 v[190:191], v[20:21], v[24:25]
	v_pk_add_f32 v[188:189], v[18:19], v[22:23] neg_lo:[0,1] neg_hi:[0,1]
	v_pk_add_f32 v[192:193], v[20:21], v[24:25] neg_lo:[0,1] neg_hi:[0,1]
	v_pk_add_f32 v[18:19], v[26:27], v[190:191]
	v_pk_add_f32 v[22:23], v[26:27], v[190:191] neg_lo:[0,1] neg_hi:[0,1]
	v_pk_add_f32 v[20:21], v[188:189], v[192:193] op_sel:[0,1] op_sel_hi:[1,0] neg_lo:[0,1]
	v_pk_add_f32 v[24:25], v[188:189], v[192:193] op_sel:[0,1] op_sel_hi:[1,0] neg_hi:[0,1]
	s_nop 0
	ds_write_b128 v17, v[18:21]
	ds_write_b128 v17, v[22:25] offset:16
	v_add_u32_e32 v230, 0x200, v3
	v_mov_b32_e32 v3, v230
	s_nop 0
	v_lshlrev_b32_e32 v219, 3, v218
	v_and_b32_e32 v220, 0xffe0, v219
	global_load_dwordx4 v[230:233], v220, s[80:81] offset:16
	global_load_dwordx4 v[234:237], v220, s[80:81]
	v_add_u32_e32 v218, 0x800, v218
	v_ashrrev_i32_e32 v4, 31, v3
	v_lshrrev_b32_e32 v4, 21, v4
	v_add_lshl_u32 v4, v3, v4, 5
	v_and_b32_e32 v12, 0xffff0000, v4
	v_lshlrev_b32_e32 v4, 3, v2
	v_and_b32_e32 v13, 0xffe0, v4
	s_nop 0
	v_add3_u32 v17, 16, v12, v13
	ds_read_b128 v[18:21], v17
	ds_read_b128 v[22:25], v17 offset:16
	s_nop 0
	v_add_u32_e32 v2, 0x800, v2
	s_nop 0
	s_waitcnt vmcnt(4) lgkmcnt(0)
; DI float2 twid(float r) { return float2{__builtin_amdgcn_cosf(r), -__builtin_amdgcn_sinf(r)}; }
; DI void bfly_inv(float2 s0, float2 s1, float2 s2, float2 s3, float r, float2& o0, float2& o1, float2& o2, float2& o3) {
;   float2 w1 = twid(r), w2 = cmul(w1, w1), w3 = cmul(w2, w1);
;   float2 c0 = s0, c1 = cmulc(s1, w1), c2 = cmulc(s2, w2), c3 = cmulc(s3, w3);
;   float2 t0 = {c0.x + c2.x, c0.y + c2.y}, t1 = {c0.x - c2.x, c0.y - c2.y}, t2 = {c1.x + c3.x, c1.y + c3.y}, t3 = {c1.x - c3.x, c1.y - c3.y};
;   o0 = float2{t0.x + t2.x, t0.y + t2.y}; o2 = float2{t0.x - t2.x, t0.y - t2.y}; o1 = float2{t1.x - t3.y, t1.y + t3.x}; o3 = float2{t1.x + t3.y, t1.y - t3.x};
; }
;   for (int bb = tid; bb < NBT * (N / 4); bb += NTHR) { const int b = bb & (N / 4 - 1); float2* z = z0 + (bb / (N / 4)) * N; const int base = b * 4; f32x4 k01 = *(const f32x4*)(kh + base), k23 = *(const f32x4*)(kh + base + 2); float2 o0, o1, o2, o3;
;     bfly_inv(cmul(z[base], float2{k01[0], k01[1]}), cmul(z[base + 1], float2{k01[2], k01[3]}), cmul(z[base + 2], float2{k23[0], k23[1]}), cmul(z[base + 3], float2{k23[2], k23[3]}), 0.f, o0, o1, o2, o3);
;     z[base] = o0; z[base + 1] = o1; z[base + 2] = o2; z[base + 3] = o3; }
;   __syncthreads();
	v_pk_mul_f32 v[214:215], v[18:19], v[246:247] op_sel:[1,1] op_sel_hi:[1,0]
	v_pk_mul_f32 v[216:217], v[20:21], v[248:249] op_sel:[1,1] op_sel_hi:[1,0]
	v_pk_fma_f32 v[18:19], v[18:19], v[246:247], v[214:215] op_sel_hi:[0,1,1] neg_lo:[0,0,1]
	v_pk_fma_f32 v[20:21], v[20:21], v[248:249], v[216:217] op_sel_hi:[0,1,1] neg_lo:[0,0,1]
	v_pk_mul_f32 v[214:215], v[22:23], v[242:243] op_sel:[1,1] op_sel_hi:[1,0]
	v_pk_mul_f32 v[216:217], v[24:25], v[244:245] op_sel:[1,1] op_sel_hi:[1,0]
	v_pk_fma_f32 v[22:23], v[22:23], v[242:243], v[214:215] op_sel_hi:[0,1,1] neg_lo:[0,0,1]
	v_pk_fma_f32 v[24:25], v[24:25], v[244:245], v[216:217] op_sel_hi:[0,1,1] neg_lo:[0,0,1]
	v_pk_add_f32 v[26:27], v[18:19], v[22:23]
	v_pk_add_f32 v[190:191], v[20:21], v[24:25]
	v_pk_add_f32 v[188:189], v[18:19], v[22:23] neg_lo:[0,1] neg_hi:[0,1]
	v_pk_add_f32 v[192:193], v[20:21], v[24:25] neg_lo:[0,1] neg_hi:[0,1]
	v_pk_add_f32 v[18:19], v[26:27], v[190:191]
	v_pk_add_f32 v[22:23], v[26:27], v[190:191] neg_lo:[0,1] neg_hi:[0,1]
	v_pk_add_f32 v[20:21], v[188:189], v[192:193] op_sel:[0,1] op_sel_hi:[1,0] neg_lo:[0,1]
	v_pk_add_f32 v[24:25], v[188:189], v[192:193] op_sel:[0,1] op_sel_hi:[1,0] neg_hi:[0,1]
	s_nop 0
	ds_write_b128 v17, v[18:21]
	ds_write_b128 v17, v[22:25] offset:16
	v_add_u32_e32 v242, 0x200, v3
	v_mov_b32_e32 v3, v242
	s_nop 0
	v_lshlrev_b32_e32 v219, 3, v218
	v_and_b32_e32 v220, 0xffe0, v219
	global_load_dwordx4 v[242:245], v220, s[80:81] offset:16
	global_load_dwordx4 v[246:249], v220, s[80:81]
	v_add_u32_e32 v218, 0x800, v218
	v_ashrrev_i32_e32 v4, 31, v3
	v_lshrrev_b32_e32 v4, 21, v4
	v_add_lshl_u32 v4, v3, v4, 5
	v_and_b32_e32 v12, 0xffff0000, v4
	v_lshlrev_b32_e32 v4, 3, v2
	v_and_b32_e32 v13, 0xffe0, v4
	s_nop 0
	v_add3_u32 v17, 16, v12, v13
	ds_read_b128 v[18:21], v17
	ds_read_b128 v[22:25], v17 offset:16
	s_nop 0
	v_add_u32_e32 v2, 0x800, v2
	s_nop 0
	s_waitcnt vmcnt(4) lgkmcnt(0)
	v_pk_mul_f32 v[214:215], v[18:19], v[226:227] op_sel:[1,1] op_sel_hi:[1,0]
	v_pk_mul_f32 v[216:217], v[20:21], v[228:229] op_sel:[1,1] op_sel_hi:[1,0]
	v_pk_fma_f32 v[18:19], v[18:19], v[226:227], v[214:215] op_sel_hi:[0,1,1] neg_lo:[0,0,1]
	v_pk_fma_f32 v[20:21], v[20:21], v[228:229], v[216:217] op_sel_hi:[0,1,1] neg_lo:[0,0,1]
	v_pk_mul_f32 v[214:215], v[22:23], v[222:223] op_sel:[1,1] op_sel_hi:[1,0]
	v_pk_mul_f32 v[216:217], v[24:25], v[224:225] op_sel:[1,1] op_sel_hi:[1,0]
	v_pk_fma_f32 v[22:23], v[22:23], v[222:223], v[214:215] op_sel_hi:[0,1,1] neg_lo:[0,0,1]
	v_pk_fma_f32 v[24:25], v[24:25], v[224:225], v[216:217] op_sel_hi:[0,1,1] neg_lo:[0,0,1]
	v_pk_add_f32 v[26:27], v[18:19], v[22:23]
	v_pk_add_f32 v[190:191], v[20:21], v[24:25]
	v_pk_add_f32 v[188:189], v[18:19], v[22:23] neg_lo:[0,1] neg_hi:[0,1]
	v_pk_add_f32 v[192:193], v[20:21], v[24:25] neg_lo:[0,1] neg_hi:[0,1]
	v_pk_add_f32 v[18:19], v[26:27], v[190:191]
	v_pk_add_f32 v[22:23], v[26:27], v[190:191] neg_lo:[0,1] neg_hi:[0,1]
	v_pk_add_f32 v[20:21], v[188:189], v[192:193] op_sel:[0,1] op_sel_hi:[1,0] neg_lo:[0,1]
	v_pk_add_f32 v[24:25], v[188:189], v[192:193] op_sel:[0,1] op_sel_hi:[1,0] neg_hi:[0,1]
	s_nop 0
	ds_write_b128 v17, v[18:21]
	ds_write_b128 v17, v[22:25] offset:16
	v_add_u32_e32 v222, 0x200, v3
	v_mov_b32_e32 v3, v222
	s_nop 0
	v_lshlrev_b32_e32 v219, 3, v218
	v_and_b32_e32 v220, 0xffe0, v219
	global_load_dwordx4 v[222:225], v220, s[80:81] offset:16
	global_load_dwordx4 v[226:229], v220, s[80:81]
	v_add_u32_e32 v218, 0x800, v218
	v_ashrrev_i32_e32 v4, 31, v3
	v_lshrrev_b32_e32 v4, 21, v4
	v_add_lshl_u32 v4, v3, v4, 5
	v_and_b32_e32 v12, 0xffff0000, v4
	v_lshlrev_b32_e32 v4, 3, v2
	v_and_b32_e32 v13, 0xffe0, v4
	s_nop 0
	v_add3_u32 v17, 16, v12, v13
	ds_read_b128 v[18:21], v17
	ds_read_b128 v[22:25], v17 offset:16
	s_nop 0
	v_add_u32_e32 v2, 0x800, v2
	s_nop 0
	s_waitcnt vmcnt(4) lgkmcnt(0)
	v_pk_mul_f32 v[214:215], v[18:19], v[234:235] op_sel:[1,1] op_sel_hi:[1,0]
	v_pk_mul_f32 v[216:217], v[20:21], v[236:237] op_sel:[1,1] op_sel_hi:[1,0]
	v_pk_fma_f32 v[18:19], v[18:19], v[234:235], v[214:215] op_sel_hi:[0,1,1] neg_lo:[0,0,1]
	v_pk_fma_f32 v[20:21], v[20:21], v[236:237], v[216:217] op_sel_hi:[0,1,1] neg_lo:[0,0,1]
	v_pk_mul_f32 v[214:215], v[22:23], v[230:231] op_sel:[1,1] op_sel_hi:[1,0]
	v_pk_mul_f32 v[216:217], v[24:25], v[232:233] op_sel:[1,1] op_sel_hi:[1,0]
	v_pk_fma_f32 v[22:23], v[22:23], v[230:231], v[214:215] op_sel_hi:[0,1,1] neg_lo:[0,0,1]
	v_pk_fma_f32 v[24:25], v[24:25], v[232:233], v[216:217] op_sel_hi:[0,1,1] neg_lo:[0,0,1]
	v_pk_add_f32 v[26:27], v[18:19], v[22:23]
	v_pk_add_f32 v[190:191], v[20:21], v[24:25]
	v_pk_add_f32 v[188:189], v[18:19], v[22:23] neg_lo:[0,1] neg_hi:[0,1]
	v_pk_add_f32 v[192:193], v[20:21], v[24:25] neg_lo:[0,1] neg_hi:[0,1]
	v_pk_add_f32 v[18:19], v[26:27], v[190:191]
	v_pk_add_f32 v[22:23], v[26:27], v[190:191] neg_lo:[0,1] neg_hi:[0,1]
	v_pk_add_f32 v[20:21], v[188:189], v[192:193] op_sel:[0,1] op_sel_hi:[1,0] neg_lo:[0,1]
	v_pk_add_f32 v[24:25], v[188:189], v[192:193] op_sel:[0,1] op_sel_hi:[1,0] neg_hi:[0,1]
	s_nop 0
	ds_write_b128 v17, v[18:21]
	ds_write_b128 v17, v[22:25] offset:16
	v_add_u32_e32 v230, 0x200, v3
	v_mov_b32_e32 v3, v230
	s_nop 0
	v_lshlrev_b32_e32 v219, 3, v218
	v_and_b32_e32 v220, 0xffe0, v219
	global_load_dwordx4 v[230:233], v220, s[80:81] offset:16
	global_load_dwordx4 v[234:237], v220, s[80:81]
	v_add_u32_e32 v218, 0x800, v218
	v_ashrrev_i32_e32 v4, 31, v3
	v_lshrrev_b32_e32 v4, 21, v4
	v_add_lshl_u32 v4, v3, v4, 5
	v_and_b32_e32 v12, 0xffff0000, v4
	v_lshlrev_b32_e32 v4, 3, v2
	v_and_b32_e32 v13, 0xffe0, v4
	s_nop 0
	v_add3_u32 v17, 16, v12, v13
	ds_read_b128 v[18:21], v17
	ds_read_b128 v[22:25], v17 offset:16
	s_nop 0
	v_add_u32_e32 v2, 0x800, v2
	s_nop 0
	s_waitcnt vmcnt(4) lgkmcnt(0)
; DI float2 twid(float r) { return float2{__builtin_amdgcn_cosf(r), -__builtin_amdgcn_sinf(r)}; }
; DI void bfly_inv(float2 s0, float2 s1, float2 s2, float2 s3, float r, float2& o0, float2& o1, float2& o2, float2& o3) {
;   float2 w1 = twid(r), w2 = cmul(w1, w1), w3 = cmul(w2, w1);
;   float2 c0 = s0, c1 = cmulc(s1, w1), c2 = cmulc(s2, w2), c3 = cmulc(s3, w3);
;   float2 t0 = {c0.x + c2.x, c0.y + c2.y}, t1 = {c0.x - c2.x, c0.y - c2.y}, t2 = {c1.x + c3.x, c1.y + c3.y}, t3 = {c1.x - c3.x, c1.y - c3.y};
;   o0 = float2{t0.x + t2.x, t0.y + t2.y}; o2 = float2{t0.x - t2.x, t0.y - t2.y}; o1 = float2{t1.x - t3.y, t1.y + t3.x}; o3 = float2{t1.x + t3.y, t1.y - t3.x};
; }
;   for (int bb = tid; bb < NBT * (N / 4); bb += NTHR) { const int b = bb & (N / 4 - 1); float2* z = z0 + (bb / (N / 4)) * N; const int base = b * 4; f32x4 k01 = *(const f32x4*)(kh + base), k23 = *(const f32x4*)(kh + base + 2); float2 o0, o1, o2, o3;
;     bfly_inv(cmul(z[base], float2{k01[0], k01[1]}), cmul(z[base + 1], float2{k01[2], k01[3]}), cmul(z[base + 2], float2{k23[0], k23[1]}), cmul(z[base + 3], float2{k23[2], k23[3]}), 0.f, o0, o1, o2, o3);
;     z[base] = o0; z[base + 1] = o1; z[base + 2] = o2; z[base + 3] = o3; }
;   __syncthreads();
	v_pk_mul_f32 v[214:215], v[18:19], v[246:247] op_sel:[1,1] op_sel_hi:[1,0]
	v_pk_mul_f32 v[216:217], v[20:21], v[248:249] op_sel:[1,1] op_sel_hi:[1,0]
	v_pk_fma_f32 v[18:19], v[18:19], v[246:247], v[214:215] op_sel_hi:[0,1,1] neg_lo:[0,0,1]
	v_pk_fma_f32 v[20:21], v[20:21], v[248:249], v[216:217] op_sel_hi:[0,1,1] neg_lo:[0,0,1]
	v_pk_mul_f32 v[214:215], v[22:23], v[242:243] op_sel:[1,1] op_sel_hi:[1,0]
	v_pk_mul_f32 v[216:217], v[24:25], v[244:245] op_sel:[1,1] op_sel_hi:[1,0]
	v_pk_fma_f32 v[22:23], v[22:23], v[242:243], v[214:215] op_sel_hi:[0,1,1] neg_lo:[0,0,1]
	v_pk_fma_f32 v[24:25], v[24:25], v[244:245], v[216:217] op_sel_hi:[0,1,1] neg_lo:[0,0,1]
	v_pk_add_f32 v[26:27], v[18:19], v[22:23]
	v_pk_add_f32 v[190:191], v[20:21], v[24:25]
	v_pk_add_f32 v[188:189], v[18:19], v[22:23] neg_lo:[0,1] neg_hi:[0,1]
	v_pk_add_f32 v[192:193], v[20:21], v[24:25] neg_lo:[0,1] neg_hi:[0,1]
	v_pk_add_f32 v[18:19], v[26:27], v[190:191]
	v_pk_add_f32 v[22:23], v[26:27], v[190:191] neg_lo:[0,1] neg_hi:[0,1]
	v_pk_add_f32 v[20:21], v[188:189], v[192:193] op_sel:[0,1] op_sel_hi:[1,0] neg_lo:[0,1]
	v_pk_add_f32 v[24:25], v[188:189], v[192:193] op_sel:[0,1] op_sel_hi:[1,0] neg_hi:[0,1]
	s_nop 0
	ds_write_b128 v17, v[18:21]
	ds_write_b128 v17, v[22:25] offset:16
	v_add_u32_e32 v242, 0x200, v3
	v_mov_b32_e32 v3, v242
	s_nop 0
	v_ashrrev_i32_e32 v4, 31, v3
	v_lshrrev_b32_e32 v4, 21, v4
	v_add_lshl_u32 v4, v3, v4, 5
	v_and_b32_e32 v12, 0xffff0000, v4
	v_lshlrev_b32_e32 v4, 3, v2
	v_and_b32_e32 v13, 0xffe0, v4
	s_nop 0
	v_add3_u32 v17, 16, v12, v13
	ds_read_b128 v[18:21], v17
	ds_read_b128 v[22:25], v17 offset:16
	s_nop 0
	v_add_u32_e32 v2, 0x800, v2
	s_nop 0
	s_waitcnt vmcnt(2) lgkmcnt(0)
	v_pk_mul_f32 v[214:215], v[18:19], v[226:227] op_sel:[1,1] op_sel_hi:[1,0]
	v_pk_mul_f32 v[216:217], v[20:21], v[228:229] op_sel:[1,1] op_sel_hi:[1,0]
	v_pk_fma_f32 v[18:19], v[18:19], v[226:227], v[214:215] op_sel_hi:[0,1,1] neg_lo:[0,0,1]
	v_pk_fma_f32 v[20:21], v[20:21], v[228:229], v[216:217] op_sel_hi:[0,1,1] neg_lo:[0,0,1]
	v_pk_mul_f32 v[214:215], v[22:23], v[222:223] op_sel:[1,1] op_sel_hi:[1,0]
	v_pk_mul_f32 v[216:217], v[24:25], v[224:225] op_sel:[1,1] op_sel_hi:[1,0]
	v_pk_fma_f32 v[22:23], v[22:23], v[222:223], v[214:215] op_sel_hi:[0,1,1] neg_lo:[0,0,1]
	v_pk_fma_f32 v[24:25], v[24:25], v[224:225], v[216:217] op_sel_hi:[0,1,1] neg_lo:[0,0,1]
	v_pk_add_f32 v[26:27], v[18:19], v[22:23]
	v_pk_add_f32 v[190:191], v[20:21], v[24:25]
	v_pk_add_f32 v[188:189], v[18:19], v[22:23] neg_lo:[0,1] neg_hi:[0,1]
	v_pk_add_f32 v[192:193], v[20:21], v[24:25] neg_lo:[0,1] neg_hi:[0,1]
	v_pk_add_f32 v[18:19], v[26:27], v[190:191]
	v_pk_add_f32 v[22:23], v[26:27], v[190:191] neg_lo:[0,1] neg_hi:[0,1]
	v_pk_add_f32 v[20:21], v[188:189], v[192:193] op_sel:[0,1] op_sel_hi:[1,0] neg_lo:[0,1]
	v_pk_add_f32 v[24:25], v[188:189], v[192:193] op_sel:[0,1] op_sel_hi:[1,0] neg_hi:[0,1]
	s_nop 0
	ds_write_b128 v17, v[18:21]
	ds_write_b128 v17, v[22:25] offset:16
	v_add_u32_e32 v222, 0x200, v3
	v_mov_b32_e32 v3, v222
	s_nop 0
	v_ashrrev_i32_e32 v4, 31, v3
	v_lshrrev_b32_e32 v4, 21, v4
	v_add_lshl_u32 v4, v3, v4, 5
	v_and_b32_e32 v12, 0xffff0000, v4
	v_lshlrev_b32_e32 v4, 3, v2
	v_and_b32_e32 v13, 0xffe0, v4
	s_nop 0
	v_add3_u32 v17, 16, v12, v13
	ds_read_b128 v[18:21], v17
	ds_read_b128 v[22:25], v17 offset:16
	s_nop 0
	v_add_u32_e32 v2, 0x800, v2
	s_nop 0
	s_waitcnt vmcnt(0) lgkmcnt(0)
	v_pk_mul_f32 v[214:215], v[18:19], v[234:235] op_sel:[1,1] op_sel_hi:[1,0]
	v_pk_mul_f32 v[216:217], v[20:21], v[236:237] op_sel:[1,1] op_sel_hi:[1,0]
	v_pk_fma_f32 v[18:19], v[18:19], v[234:235], v[214:215] op_sel_hi:[0,1,1] neg_lo:[0,0,1]
	v_pk_fma_f32 v[20:21], v[20:21], v[236:237], v[216:217] op_sel_hi:[0,1,1] neg_lo:[0,0,1]
	v_pk_mul_f32 v[214:215], v[22:23], v[230:231] op_sel:[1,1] op_sel_hi:[1,0]
	v_pk_mul_f32 v[216:217], v[24:25], v[232:233] op_sel:[1,1] op_sel_hi:[1,0]
	v_pk_fma_f32 v[22:23], v[22:23], v[230:231], v[214:215] op_sel_hi:[0,1,1] neg_lo:[0,0,1]
	v_pk_fma_f32 v[24:25], v[24:25], v[232:233], v[216:217] op_sel_hi:[0,1,1] neg_lo:[0,0,1]
	v_pk_add_f32 v[26:27], v[18:19], v[22:23]
	v_pk_add_f32 v[190:191], v[20:21], v[24:25]
	v_pk_add_f32 v[188:189], v[18:19], v[22:23] neg_lo:[0,1] neg_hi:[0,1]
	v_pk_add_f32 v[192:193], v[20:21], v[24:25] neg_lo:[0,1] neg_hi:[0,1]
	v_pk_add_f32 v[18:19], v[26:27], v[190:191]
	v_pk_add_f32 v[22:23], v[26:27], v[190:191] neg_lo:[0,1] neg_hi:[0,1]
	v_pk_add_f32 v[20:21], v[188:189], v[192:193] op_sel:[0,1] op_sel_hi:[1,0] neg_lo:[0,1]
	v_pk_add_f32 v[24:25], v[188:189], v[192:193] op_sel:[0,1] op_sel_hi:[1,0] neg_hi:[0,1]
	s_nop 0
	ds_write_b128 v17, v[18:21]
	ds_write_b128 v17, v[22:25] offset:16
	v_add_u32_e32 v230, 0x200, v3
	v_mov_b32_e32 v3, v230
	s_nop 0
	s_mov_b64 s[84:85], exec

; DI float2 twid(float r) { return float2{__builtin_amdgcn_cosf(r), -__builtin_amdgcn_sinf(r)}; }
; DI void bfly_fwd(float2 a0, float2 a1, float2 a2, float2 a3, float r, float2& o0, float2& o1, float2& o2, float2& o3) {
;   float2 t0 = {a0.x + a2.x, a0.y + a2.y}, t1 = {a0.x - a2.x, a0.y - a2.y}, t2 = {a1.x + a3.x, a1.y + a3.y}, t3 = {a1.x - a3.x, a1.y - a3.y};
;   float2 b0 = {t0.x + t2.x, t0.y + t2.y}, b2 = {t0.x - t2.x, t0.y - t2.y}, b1 = {t1.x + t3.y, t1.y - t3.x}, b3 = {t1.x - t3.y, t1.y + t3.x};
;   float2 w1 = twid(r), w2 = cmul(w1, w1), w3 = cmul(w2, w1);
;   o0 = b0; o1 = cmul(b1, w1); o2 = cmul(b2, w2); o3 = cmul(b3, w3);
; }
;   const int Q = 1 << lq; const float invM = 1.f / (float)(4 << lq);
;   for (int bb = tid; bb < NBT * (N / 4); bb += NTHR) { const int b = bb & (N / 4 - 1); float2* z = z0 + (bb / (N / 4)) * N; int j = b & (Q - 1), base = ((b >> lq) << (lq + 2)) + j; float2 o0, o1, o2, o3;
;     bfly_fwd(z[base], z[base + Q], z[base + 2 * Q], z[base + 3 * Q], (float)j * invM, o0, o1, o2, o3);
;     z[base] = o0; z[base + Q] = o1; z[base + 2 * Q] = o2; z[base + 3 * Q] = o3; }
;   __syncthreads();
; }
.LBB0_1641:
	v_ashrrev_i32_e32 v6, 31, v5
	v_lshrrev_b32_e32 v6, 20, v6
	v_add_lshl_u32 v6, v5, v6, 5
	v_and_b32_e32 v7, 0x3ffc, v4
	v_and_b32_e32 v6, 0xfffe0000, v6
	v_lshlrev_b32_e32 v7, 3, v7
	v_add3_u32 v19, 16, v6, v7
	ds_read_b128 v[6:9], v19
	ds_read_b128 v[10:13], v19 offset:16
	v_cmp_lt_i32_e64 s[14:15], s25, v5
	v_add_u32_e32 v4, 0x800, v4
	s_or_b64 s[80:81], s[14:15], s[80:81]
	s_waitcnt lgkmcnt(0)
	v_pk_add_f32 v[14:15], v[6:7], v[10:11]
	v_pk_add_f32 v[22:23], v[8:9], v[12:13]
	v_pk_add_f32 v[20:21], v[6:7], v[10:11] neg_lo:[0,1] neg_hi:[0,1]
	v_pk_add_f32 v[24:25], v[8:9], v[12:13] neg_lo:[0,1] neg_hi:[0,1]
	v_pk_add_f32 v[6:7], v[14:15], v[22:23]
	v_pk_add_f32 v[10:11], v[14:15], v[22:23] neg_lo:[0,1] neg_hi:[0,1]
	v_pk_add_f32 v[8:9], v[20:21], v[24:25] op_sel:[0,1] op_sel_hi:[1,0] neg_hi:[0,1]
	v_pk_add_f32 v[12:13], v[20:21], v[24:25] op_sel:[0,1] op_sel_hi:[1,0] neg_lo:[0,1]
	s_nop 0
	ds_write_b128 v19, v[6:9]
	ds_write_b128 v19, v[10:13] offset:16
	v_add_u32_e32 v6, 0x200, v5
	v_mov_b32_e32 v5, v6
	s_andn2_b64 exec, exec, s[80:81]
	s_cbranch_execnz .LBB0_1641

; DI float2 twid(float r) { return float2{__builtin_amdgcn_cosf(r), -__builtin_amdgcn_sinf(r)}; }
; DI void bfly_inv(float2 s0, float2 s1, float2 s2, float2 s3, float r, float2& o0, float2& o1, float2& o2, float2& o3) {
;   float2 w1 = twid(r), w2 = cmul(w1, w1), w3 = cmul(w2, w1);
;   float2 c0 = s0, c1 = cmulc(s1, w1), c2 = cmulc(s2, w2), c3 = cmulc(s3, w3);
;   float2 t0 = {c0.x + c2.x, c0.y + c2.y}, t1 = {c0.x - c2.x, c0.y - c2.y}, t2 = {c1.x + c3.x, c1.y + c3.y}, t3 = {c1.x - c3.x, c1.y - c3.y};
;   o0 = float2{t0.x + t2.x, t0.y + t2.y}; o2 = float2{t0.x - t2.x, t0.y - t2.y}; o1 = float2{t1.x - t3.y, t1.y + t3.x}; o3 = float2{t1.x + t3.y, t1.y - t3.x};
; }
;   for (int bb = tid; bb < NBT * (N / 4); bb += NTHR) { const int b = bb & (N / 4 - 1); float2* z = z0 + (bb / (N / 4)) * N; const int base = b * 4; f32x4 k01 = *(const f32x4*)(kh + base), k23 = *(const f32x4*)(kh + base + 2); float2 o0, o1, o2, o3;
;     bfly_inv(cmul(z[base], float2{k01[0], k01[1]}), cmul(z[base + 1], float2{k01[2], k01[3]}), cmul(z[base + 2], float2{k23[0], k23[1]}), cmul(z[base + 3], float2{k23[2], k23[3]}), 0.f, o0, o1, o2, o3);
;     z[base] = o0; z[base + 1] = o1; z[base + 2] = o2; z[base + 3] = o3; }
;   __syncthreads();
.LBB0_1644:
	v_mov_b32_e32 v218, v4
	v_lshlrev_b32_e32 v219, 3, v218
	v_and_b32_e32 v220, 0x1ffe0, v219
	global_load_dwordx4 v[222:225], v220, s[80:81] offset:16
	global_load_dwordx4 v[226:229], v220, s[80:81]
	v_add_u32_e32 v218, 0x800, v218
	v_lshlrev_b32_e32 v219, 3, v218
	v_and_b32_e32 v220, 0x1ffe0, v219
	global_load_dwordx4 v[230:233], v220, s[80:81] offset:16
	global_load_dwordx4 v[234:237], v220, s[80:81]
	v_add_u32_e32 v218, 0x800, v218
	v_lshlrev_b32_e32 v219, 3, v218
	v_and_b32_e32 v220, 0x1ffe0, v219
	global_load_dwordx4 v[242:245], v220, s[80:81] offset:16
	global_load_dwordx4 v[246:249], v220, s[80:81]
	v_add_u32_e32 v218, 0x800, v218
	v_ashrrev_i32_e32 v6, 31, v5
	v_lshrrev_b32_e32 v6, 20, v6
	v_add_lshl_u32 v6, v5, v6, 5
	v_and_b32_e32 v14, 0xfffe0000, v6
	v_lshlrev_b32_e32 v6, 3, v4
	v_and_b32_e32 v15, 0x1ffe0, v6
	s_nop 0
	v_add3_u32 v19, 16, v14, v15
	ds_read_b128 v[20:23], v19
	ds_read_b128 v[24:27], v19 offset:16
	s_nop 0
	v_add_u32_e32 v4, 0x800, v4
	s_nop 0
	s_waitcnt vmcnt(4) lgkmcnt(0)
	v_pk_mul_f32 v[214:215], v[20:21], v[226:227] op_sel:[1,1] op_sel_hi:[1,0]
	v_pk_mul_f32 v[216:217], v[22:23], v[228:229] op_sel:[1,1] op_sel_hi:[1,0]
	v_pk_fma_f32 v[20:21], v[20:21], v[226:227], v[214:215] op_sel_hi:[0,1,1] neg_lo:[0,0,1]
	v_pk_fma_f32 v[22:23], v[22:23], v[228:229], v[216:217] op_sel_hi:[0,1,1] neg_lo:[0,0,1]
	v_pk_mul_f32 v[214:215], v[24:25], v[222:223] op_sel:[1,1] op_sel_hi:[1,0]
	v_pk_mul_f32 v[216:217], v[26:27], v[224:225] op_sel:[1,1] op_sel_hi:[1,0]
	v_pk_fma_f32 v[24:25], v[24:25], v[222:223], v[214:215] op_sel_hi:[0,1,1] neg_lo:[0,0,1]
	v_pk_fma_f32 v[26:27], v[26:27], v[224:225], v[216:217] op_sel_hi:[0,1,1] neg_lo:[0,0,1]
	v_pk_add_f32 v[28:29], v[20:21], v[24:25]
	v_pk_add_f32 v[190:191], v[22:23], v[26:27]
	v_pk_add_f32 v[188:189], v[20:21], v[24:25] neg_lo:[0,1] neg_hi:[0,1]
	v_pk_add_f32 v[192:193], v[22:23], v[26:27] neg_lo:[0,1] neg_hi:[0,1]
	v_pk_add_f32 v[20:21], v[28:29], v[190:191]
	v_pk_add_f32 v[24:25], v[28:29], v[190:191] neg_lo:[0,1] neg_hi:[0,1]
	v_pk_add_f32 v[22:23], v[188:189], v[192:193] op_sel:[0,1] op_sel_hi:[1,0] neg_lo:[0,1]
	v_pk_add_f32 v[26:27], v[188:189], v[192:193] op_sel:[0,1] op_sel_hi:[1,0] neg_hi:[0,1]
	s_nop 0
	ds_write_b128 v19, v[20:23]
	ds_write_b128 v19, v[24:27] offset:16
	v_add_u32_e32 v222, 0x200, v5
	v_mov_b32_e32 v5, v222
	s_nop 0
	v_lshlrev_b32_e32 v219, 3, v218
	v_and_b32_e32 v220, 0x1ffe0, v219
	global_load_dwordx4 v[222:225], v220, s[80:81] offset:16
	global_load_dwordx4 v[226:229], v220, s[80:81]
	v_add_u32_e32 v218, 0x800, v218
	v_ashrrev_i32_e32 v6, 31, v5
	v_lshrrev_b32_e32 v6, 20, v6
	v_add_lshl_u32 v6, v5, v6, 5
	v_and_b32_e32 v14, 0xfffe0000, v6
	v_lshlrev_b32_e32 v6, 3, v4
	v_and_b32_e32 v15, 0x1ffe0, v6
	s_nop 0
	v_add3_u32 v19, 16, v14, v15
	ds_read_b128 v[20:23], v19
	ds_read_b128 v[24:27], v19 offset:16
	s_nop 0
	v_add_u32_e32 v4, 0x800, v4
	s_nop 0
	s_waitcnt vmcnt(4) lgkmcnt(0)
	v_pk_mul_f32 v[214:215], v[20:21], v[234:235] op_sel:[1,1] op_sel_hi:[1,0]
	v_pk_mul_f32 v[216:217], v[22:23], v[236:237] op_sel:[1,1] op_sel_hi:[1,0]
	v_pk_fma_f32 v[20:21], v[20:21], v[234:235], v[214:215] op_sel_hi:[0,1,1] neg_lo:[0,0,1]
	v_pk_fma_f32 v[22:23], v[22:23], v[236:237], v[216:217] op_sel_hi:[0,1,1] neg_lo:[0,0,1]
	v_pk_mul_f32 v[214:215], v[24:25], v[230:231] op_sel:[1,1] op_sel_hi:[1,0]
	v_pk_mul_f32 v[216:217], v[26:27], v[232:233] op_sel:[1,1] op_sel_hi:[1,0]
	v_pk_fma_f32 v[24:25], v[24:25], v[230:231], v[214:215] op_sel_hi:[0,1,1] neg_lo:[0,0,1]
	v_pk_fma_f32 v[26:27], v[26:27], v[232:233], v[216:217] op_sel_hi:[0,1,1] neg_lo:[0,0,1]
	v_pk_add_f32 v[28:29], v[20:21], v[24:25]
	v_pk_add_f32 v[190:191], v[22:23], v[26:27]
	v_pk_add_f32 v[188:189], v[20:21], v[24:25] neg_lo:[0,1] neg_hi:[0,1]
	v_pk_add_f32 v[192:193], v[22:23], v[26:27] neg_lo:[0,1] neg_hi:[0,1]
	v_pk_add_f32 v[20:21], v[28:29], v[190:191]
	v_pk_add_f32 v[24:25], v[28:29], v[190:191] neg_lo:[0,1] neg_hi:[0,1]
	v_pk_add_f32 v[22:23], v[188:189], v[192:193] op_sel:[0,1] op_sel_hi:[1,0] neg_lo:[0,1]
	v_pk_add_f32 v[26:27], v[188:189], v[192:193] op_sel:[0,1] op_sel_hi:[1,0] neg_hi:[0,1]
	s_nop 0
	ds_write_b128 v19, v[20:23]
	ds_write_b128 v19, v[24:27] offset:16
	v_add_u32_e32 v230, 0x200, v5
	v_mov_b32_e32 v5, v230
	s_nop 0
	v_lshlrev_b32_e32 v219, 3, v218
	v_and_b32_e32 v220, 0x1ffe0, v219
	global_load_dwordx4 v[230:233], v220, s[80:81] offset:16
	global_load_dwordx4 v[234:237], v220, s[80:81]
	v_add_u32_e32 v218, 0x800, v218
	v_ashrrev_i32_e32 v6, 31, v5
	v_lshrrev_b32_e32 v6, 20, v6
	v_add_lshl_u32 v6, v5, v6, 5
	v_and_b32_e32 v14, 0xfffe0000, v6
	v_lshlrev_b32_e32 v6, 3, v4
	v_and_b32_e32 v15, 0x1ffe0, v6
	s_nop 0
	v_add3_u32 v19, 16, v14, v15
	ds_read_b128 v[20:23], v19
	ds_read_b128 v[24:27], v19 offset:16
	s_nop 0
	v_add_u32_e32 v4, 0x800, v4
	s_nop 0
	s_waitcnt vmcnt(4) lgkmcnt(0)
; DI float2 twid(float r) { return float2{__builtin_amdgcn_cosf(r), -__builtin_amdgcn_sinf(r)}; }
; DI void bfly_inv(float2 s0, float2 s1, float2 s2, float2 s3, float r, float2& o0, float2& o1, float2& o2, float2& o3) {
;   float2 w1 = twid(r), w2 = cmul(w1, w1), w3 = cmul(w2, w1);
;   float2 c0 = s0, c1 = cmulc(s1, w1), c2 = cmulc(s2, w2), c3 = cmulc(s3, w3);
;   float2 t0 = {c0.x + c2.x, c0.y + c2.y}, t1 = {c0.x - c2.x, c0.y - c2.y}, t2 = {c1.x + c3.x, c1.y + c3.y}, t3 = {c1.x - c3.x, c1.y - c3.y};
;   o0 = float2{t0.x + t2.x, t0.y + t2.y}; o2 = float2{t0.x - t2.x, t0.y - t2.y}; o1 = float2{t1.x - t3.y, t1.y + t3.x}; o3 = float2{t1.x + t3.y, t1.y - t3.x};
; }
;   for (int bb = tid; bb < NBT * (N / 4); bb += NTHR) { const int b = bb & (N / 4 - 1); float2* z = z0 + (bb / (N / 4)) * N; const int base = b * 4; f32x4 k01 = *(const f32x4*)(kh + base), k23 = *(const f32x4*)(kh + base + 2); float2 o0, o1, o2, o3;
;     bfly_inv(cmul(z[base], float2{k01[0], k01[1]}), cmul(z[base + 1], float2{k01[2], k01[3]}), cmul(z[base + 2], float2{k23[0], k23[1]}), cmul(z[base + 3], float2{k23[2], k23[3]}), 0.f, o0, o1, o2, o3);
;     z[base] = o0; z[base + 1] = o1; z[base + 2] = o2; z[base + 3] = o3; }
;   __syncthreads();
	v_pk_mul_f32 v[214:215], v[20:21], v[246:247] op_sel:[1,1] op_sel_hi:[1,0]
	v_pk_mul_f32 v[216:217], v[22:23], v[248:249] op_sel:[1,1] op_sel_hi:[1,0]
	v_pk_fma_f32 v[20:21], v[20:21], v[246:247], v[214:215] op_sel_hi:[0,1,1] neg_lo:[0,0,1]
	v_pk_fma_f32 v[22:23], v[22:23], v[248:249], v[216:217] op_sel_hi:[0,1,1] neg_lo:[0,0,1]
	v_pk_mul_f32 v[214:215], v[24:25], v[242:243] op_sel:[1,1] op_sel_hi:[1,0]
	v_pk_mul_f32 v[216:217], v[26:27], v[244:245] op_sel:[1,1] op_sel_hi:[1,0]
	v_pk_fma_f32 v[24:25], v[24:25], v[242:243], v[214:215] op_sel_hi:[0,1,1] neg_lo:[0,0,1]
	v_pk_fma_f32 v[26:27], v[26:27], v[244:245], v[216:217] op_sel_hi:[0,1,1] neg_lo:[0,0,1]
	v_pk_add_f32 v[28:29], v[20:21], v[24:25]
	v_pk_add_f32 v[190:191], v[22:23], v[26:27]
	v_pk_add_f32 v[188:189], v[20:21], v[24:25] neg_lo:[0,1] neg_hi:[0,1]
	v_pk_add_f32 v[192:193], v[22:23], v[26:27] neg_lo:[0,1] neg_hi:[0,1]
	v_pk_add_f32 v[20:21], v[28:29], v[190:191]
	v_pk_add_f32 v[24:25], v[28:29], v[190:191] neg_lo:[0,1] neg_hi:[0,1]
	v_pk_add_f32 v[22:23], v[188:189], v[192:193] op_sel:[0,1] op_sel_hi:[1,0] neg_lo:[0,1]
	v_pk_add_f32 v[26:27], v[188:189], v[192:193] op_sel:[0,1] op_sel_hi:[1,0] neg_hi:[0,1]
	s_nop 0
	ds_write_b128 v19, v[20:23]
	ds_write_b128 v19, v[24:27] offset:16
	v_add_u32_e32 v242, 0x200, v5
	v_mov_b32_e32 v5, v242
	s_nop 0
	v_lshlrev_b32_e32 v219, 3, v218
	v_and_b32_e32 v220, 0x1ffe0, v219
	global_load_dwordx4 v[242:245], v220, s[80:81] offset:16
	global_load_dwordx4 v[246:249], v220, s[80:81]
	v_add_u32_e32 v218, 0x800, v218
	v_ashrrev_i32_e32 v6, 31, v5
	v_lshrrev_b32_e32 v6, 20, v6
	v_add_lshl_u32 v6, v5, v6, 5
	v_and_b32_e32 v14, 0xfffe0000, v6
	v_lshlrev_b32_e32 v6, 3, v4
	v_and_b32_e32 v15, 0x1ffe0, v6
	s_nop 0
	v_add3_u32 v19, 16, v14, v15
	ds_read_b128 v[20:23], v19
	ds_read_b128 v[24:27], v19 offset:16
	s_nop 0
	v_add_u32_e32 v4, 0x800, v4
	s_nop 0
	s_waitcnt vmcnt(4) lgkmcnt(0)
	v_pk_mul_f32 v[214:215], v[20:21], v[226:227] op_sel:[1,1] op_sel_hi:[1,0]
	v_pk_mul_f32 v[216:217], v[22:23], v[228:229] op_sel:[1,1] op_sel_hi:[1,0]
	v_pk_fma_f32 v[20:21], v[20:21], v[226:227], v[214:215] op_sel_hi:[0,1,1] neg_lo:[0,0,1]
	v_pk_fma_f32 v[22:23], v[22:23], v[228:229], v[216:217] op_sel_hi:[0,1,1] neg_lo:[0,0,1]
	v_pk_mul_f32 v[214:215], v[24:25], v[222:223] op_sel:[1,1] op_sel_hi:[1,0]
	v_pk_mul_f32 v[216:217], v[26:27], v[224:225] op_sel:[1,1] op_sel_hi:[1,0]
	v_pk_fma_f32 v[24:25], v[24:25], v[222:223], v[214:215] op_sel_hi:[0,1,1] neg_lo:[0,0,1]
	v_pk_fma_f32 v[26:27], v[26:27], v[224:225], v[216:217] op_sel_hi:[0,1,1] neg_lo:[0,0,1]
	v_pk_add_f32 v[28:29], v[20:21], v[24:25]
	v_pk_add_f32 v[190:191], v[22:23], v[26:27]
	v_pk_add_f32 v[188:189], v[20:21], v[24:25] neg_lo:[0,1] neg_hi:[0,1]
	v_pk_add_f32 v[192:193], v[22:23], v[26:27] neg_lo:[0,1] neg_hi:[0,1]
	v_pk_add_f32 v[20:21], v[28:29], v[190:191]
	v_pk_add_f32 v[24:25], v[28:29], v[190:191] neg_lo:[0,1] neg_hi:[0,1]
	v_pk_add_f32 v[22:23], v[188:189], v[192:193] op_sel:[0,1] op_sel_hi:[1,0] neg_lo:[0,1]
	v_pk_add_f32 v[26:27], v[188:189], v[192:193] op_sel:[0,1] op_sel_hi:[1,0] neg_hi:[0,1]
	s_nop 0
	ds_write_b128 v19, v[20:23]
	ds_write_b128 v19, v[24:27] offset:16
	v_add_u32_e32 v222, 0x200, v5
	v_mov_b32_e32 v5, v222
	s_nop 0
	v_lshlrev_b32_e32 v219, 3, v218
	v_and_b32_e32 v220, 0x1ffe0, v219
	global_load_dwordx4 v[222:225], v220, s[80:81] offset:16
	global_load_dwordx4 v[226:229], v220, s[80:81]
	v_add_u32_e32 v218, 0x800, v218
	v_ashrrev_i32_e32 v6, 31, v5
	v_lshrrev_b32_e32 v6, 20, v6
	v_add_lshl_u32 v6, v5, v6, 5
	v_and_b32_e32 v14, 0xfffe0000, v6
	v_lshlrev_b32_e32 v6, 3, v4
	v_and_b32_e32 v15, 0x1ffe0, v6
	s_nop 0
	v_add3_u32 v19, 16, v14, v15
	ds_read_b128 v[20:23], v19
	ds_read_b128 v[24:27], v19 offset:16
	s_nop 0
	v_add_u32_e32 v4, 0x800, v4
	s_nop 0
	s_waitcnt vmcnt(4) lgkmcnt(0)
	v_pk_mul_f32 v[214:215], v[20:21], v[234:235] op_sel:[1,1] op_sel_hi:[1,0]
	v_pk_mul_f32 v[216:217], v[22:23], v[236:237] op_sel:[1,1] op_sel_hi:[1,0]
	v_pk_fma_f32 v[20:21], v[20:21], v[234:235], v[214:215] op_sel_hi:[0,1,1] neg_lo:[0,0,1]
	v_pk_fma_f32 v[22:23], v[22:23], v[236:237], v[216:217] op_sel_hi:[0,1,1] neg_lo:[0,0,1]
	v_pk_mul_f32 v[214:215], v[24:25], v[230:231] op_sel:[1,1] op_sel_hi:[1,0]
	v_pk_mul_f32 v[216:217], v[26:27], v[232:233] op_sel:[1,1] op_sel_hi:[1,0]
	v_pk_fma_f32 v[24:25], v[24:25], v[230:231], v[214:215] op_sel_hi:[0,1,1] neg_lo:[0,0,1]
	v_pk_fma_f32 v[26:27], v[26:27], v[232:233], v[216:217] op_sel_hi:[0,1,1] neg_lo:[0,0,1]
	v_pk_add_f32 v[28:29], v[20:21], v[24:25]
	v_pk_add_f32 v[190:191], v[22:23], v[26:27]
	v_pk_add_f32 v[188:189], v[20:21], v[24:25] neg_lo:[0,1] neg_hi:[0,1]
	v_pk_add_f32 v[192:193], v[22:23], v[26:27] neg_lo:[0,1] neg_hi:[0,1]
	v_pk_add_f32 v[20:21], v[28:29], v[190:191]
	v_pk_add_f32 v[24:25], v[28:29], v[190:191] neg_lo:[0,1] neg_hi:[0,1]
	v_pk_add_f32 v[22:23], v[188:189], v[192:193] op_sel:[0,1] op_sel_hi:[1,0] neg_lo:[0,1]
	v_pk_add_f32 v[26:27], v[188:189], v[192:193] op_sel:[0,1] op_sel_hi:[1,0] neg_hi:[0,1]
	s_nop 0
	ds_write_b128 v19, v[20:23]
	ds_write_b128 v19, v[24:27] offset:16
	v_add_u32_e32 v230, 0x200, v5
	v_mov_b32_e32 v5, v230
	s_nop 0
	v_lshlrev_b32_e32 v219, 3, v218
	v_and_b32_e32 v220, 0x1ffe0, v219
	global_load_dwordx4 v[230:233], v220, s[80:81] offset:16
	global_load_dwordx4 v[234:237], v220, s[80:81]
	v_add_u32_e32 v218, 0x800, v218
	v_ashrrev_i32_e32 v6, 31, v5
	v_lshrrev_b32_e32 v6, 20, v6
	v_add_lshl_u32 v6, v5, v6, 5
	v_and_b32_e32 v14, 0xfffe0000, v6
	v_lshlrev_b32_e32 v6, 3, v4
	v_and_b32_e32 v15, 0x1ffe0, v6
	s_nop 0
	v_add3_u32 v19, 16, v14, v15
	ds_read_b128 v[20:23], v19
	ds_read_b128 v[24:27], v19 offset:16
	s_nop 0
	v_add_u32_e32 v4, 0x800, v4
	s_nop 0
	s_waitcnt vmcnt(4) lgkmcnt(0)
; DI float2 twid(float r) { return float2{__builtin_amdgcn_cosf(r), -__builtin_amdgcn_sinf(r)}; }
; DI void bfly_inv(float2 s0, float2 s1, float2 s2, float2 s3, float r, float2& o0, float2& o1, float2& o2, float2& o3) {
;   float2 w1 = twid(r), w2 = cmul(w1, w1), w3 = cmul(w2, w1);
;   float2 c0 = s0, c1 = cmulc(s1, w1), c2 = cmulc(s2, w2), c3 = cmulc(s3, w3);
;   float2 t0 = {c0.x + c2.x, c0.y + c2.y}, t1 = {c0.x - c2.x, c0.y - c2.y}, t2 = {c1.x + c3.x, c1.y + c3.y}, t3 = {c1.x - c3.x, c1.y - c3.y};
;   o0 = float2{t0.x + t2.x, t0.y + t2.y}; o2 = float2{t0.x - t2.x, t0.y - t2.y}; o1 = float2{t1.x - t3.y, t1.y + t3.x}; o3 = float2{t1.x + t3.y, t1.y - t3.x};
; }
;   for (int bb = tid; bb < NBT * (N / 4); bb += NTHR) { const int b = bb & (N / 4 - 1); float2* z = z0 + (bb / (N / 4)) * N; const int base = b * 4; f32x4 k01 = *(const f32x4*)(kh + base), k23 = *(const f32x4*)(kh + base + 2); float2 o0, o1, o2, o3;
;     bfly_inv(cmul(z[base], float2{k01[0], k01[1]}), cmul(z[base + 1], float2{k01[2], k01[3]}), cmul(z[base + 2], float2{k23[0], k23[1]}), cmul(z[base + 3], float2{k23[2], k23[3]}), 0.f, o0, o1, o2, o3);
;     z[base] = o0; z[base + 1] = o1; z[base + 2] = o2; z[base + 3] = o3; }
;   __syncthreads();
	v_pk_mul_f32 v[214:215], v[20:21], v[246:247] op_sel:[1,1] op_sel_hi:[1,0]
	v_pk_mul_f32 v[216:217], v[22:23], v[248:249] op_sel:[1,1] op_sel_hi:[1,0]
	v_pk_fma_f32 v[20:21], v[20:21], v[246:247], v[214:215] op_sel_hi:[0,1,1] neg_lo:[0,0,1]
	v_pk_fma_f32 v[22:23], v[22:23], v[248:249], v[216:217] op_sel_hi:[0,1,1] neg_lo:[0,0,1]
	v_pk_mul_f32 v[214:215], v[24:25], v[242:243] op_sel:[1,1] op_sel_hi:[1,0]
	v_pk_mul_f32 v[216:217], v[26:27], v[244:245] op_sel:[1,1] op_sel_hi:[1,0]
	v_pk_fma_f32 v[24:25], v[24:25], v[242:243], v[214:215] op_sel_hi:[0,1,1] neg_lo:[0,0,1]
	v_pk_fma_f32 v[26:27], v[26:27], v[244:245], v[216:217] op_sel_hi:[0,1,1] neg_lo:[0,0,1]
	v_pk_add_f32 v[28:29], v[20:21], v[24:25]
	v_pk_add_f32 v[190:191], v[22:23], v[26:27]
	v_pk_add_f32 v[188:189], v[20:21], v[24:25] neg_lo:[0,1] neg_hi:[0,1]
	v_pk_add_f32 v[192:193], v[22:23], v[26:27] neg_lo:[0,1] neg_hi:[0,1]
	v_pk_add_f32 v[20:21], v[28:29], v[190:191]
	v_pk_add_f32 v[24:25], v[28:29], v[190:191] neg_lo:[0,1] neg_hi:[0,1]
	v_pk_add_f32 v[22:23], v[188:189], v[192:193] op_sel:[0,1] op_sel_hi:[1,0] neg_lo:[0,1]
	v_pk_add_f32 v[26:27], v[188:189], v[192:193] op_sel:[0,1] op_sel_hi:[1,0] neg_hi:[0,1]
	s_nop 0
	ds_write_b128 v19, v[20:23]
	ds_write_b128 v19, v[24:27] offset:16
	v_add_u32_e32 v242, 0x200, v5
	v_mov_b32_e32 v5, v242
	s_nop 0
	v_ashrrev_i32_e32 v6, 31, v5
	v_lshrrev_b32_e32 v6, 20, v6
	v_add_lshl_u32 v6, v5, v6, 5
	v_and_b32_e32 v14, 0xfffe0000, v6
	v_lshlrev_b32_e32 v6, 3, v4
	v_and_b32_e32 v15, 0x1ffe0, v6
	s_nop 0
	v_add3_u32 v19, 16, v14, v15
	ds_read_b128 v[20:23], v19
	ds_read_b128 v[24:27], v19 offset:16
	s_nop 0
	v_add_u32_e32 v4, 0x800, v4
	s_nop 0
	s_waitcnt vmcnt(2) lgkmcnt(0)
	v_pk_mul_f32 v[214:215], v[20:21], v[226:227] op_sel:[1,1] op_sel_hi:[1,0]
	v_pk_mul_f32 v[216:217], v[22:23], v[228:229] op_sel:[1,1] op_sel_hi:[1,0]
	v_pk_fma_f32 v[20:21], v[20:21], v[226:227], v[214:215] op_sel_hi:[0,1,1] neg_lo:[0,0,1]
	v_pk_fma_f32 v[22:23], v[22:23], v[228:229], v[216:217] op_sel_hi:[0,1,1] neg_lo:[0,0,1]
	v_pk_mul_f32 v[214:215], v[24:25], v[222:223] op_sel:[1,1] op_sel_hi:[1,0]
	v_pk_mul_f32 v[216:217], v[26:27], v[224:225] op_sel:[1,1] op_sel_hi:[1,0]
	v_pk_fma_f32 v[24:25], v[24:25], v[222:223], v[214:215] op_sel_hi:[0,1,1] neg_lo:[0,0,1]
	v_pk_fma_f32 v[26:27], v[26:27], v[224:225], v[216:217] op_sel_hi:[0,1,1] neg_lo:[0,0,1]
	v_pk_add_f32 v[28:29], v[20:21], v[24:25]
	v_pk_add_f32 v[190:191], v[22:23], v[26:27]
	v_pk_add_f32 v[188:189], v[20:21], v[24:25] neg_lo:[0,1] neg_hi:[0,1]
	v_pk_add_f32 v[192:193], v[22:23], v[26:27] neg_lo:[0,1] neg_hi:[0,1]
	v_pk_add_f32 v[20:21], v[28:29], v[190:191]
	v_pk_add_f32 v[24:25], v[28:29], v[190:191] neg_lo:[0,1] neg_hi:[0,1]
	v_pk_add_f32 v[22:23], v[188:189], v[192:193] op_sel:[0,1] op_sel_hi:[1,0] neg_lo:[0,1]
	v_pk_add_f32 v[26:27], v[188:189], v[192:193] op_sel:[0,1] op_sel_hi:[1,0] neg_hi:[0,1]
	s_nop 0
	ds_write_b128 v19, v[20:23]
	ds_write_b128 v19, v[24:27] offset:16
	v_add_u32_e32 v222, 0x200, v5
	v_mov_b32_e32 v5, v222
	s_nop 0
	v_ashrrev_i32_e32 v6, 31, v5
	v_lshrrev_b32_e32 v6, 20, v6
	v_add_lshl_u32 v6, v5, v6, 5
	v_and_b32_e32 v14, 0xfffe0000, v6
	v_lshlrev_b32_e32 v6, 3, v4
	v_and_b32_e32 v15, 0x1ffe0, v6
	s_nop 0
	v_add3_u32 v19, 16, v14, v15
	ds_read_b128 v[20:23], v19
	ds_read_b128 v[24:27], v19 offset:16
	s_nop 0
	v_add_u32_e32 v4, 0x800, v4
	s_nop 0
	s_waitcnt vmcnt(0) lgkmcnt(0)
	v_pk_mul_f32 v[214:215], v[20:21], v[234:235] op_sel:[1,1] op_sel_hi:[1,0]
	v_pk_mul_f32 v[216:217], v[22:23], v[236:237] op_sel:[1,1] op_sel_hi:[1,0]
	v_pk_fma_f32 v[20:21], v[20:21], v[234:235], v[214:215] op_sel_hi:[0,1,1] neg_lo:[0,0,1]
	v_pk_fma_f32 v[22:23], v[22:23], v[236:237], v[216:217] op_sel_hi:[0,1,1] neg_lo:[0,0,1]
	v_pk_mul_f32 v[214:215], v[24:25], v[230:231] op_sel:[1,1] op_sel_hi:[1,0]
	v_pk_mul_f32 v[216:217], v[26:27], v[232:233] op_sel:[1,1] op_sel_hi:[1,0]
	v_pk_fma_f32 v[24:25], v[24:25], v[230:231], v[214:215] op_sel_hi:[0,1,1] neg_lo:[0,0,1]
	v_pk_fma_f32 v[26:27], v[26:27], v[232:233], v[216:217] op_sel_hi:[0,1,1] neg_lo:[0,0,1]
	v_pk_add_f32 v[28:29], v[20:21], v[24:25]
	v_pk_add_f32 v[190:191], v[22:23], v[26:27]
	v_pk_add_f32 v[188:189], v[20:21], v[24:25] neg_lo:[0,1] neg_hi:[0,1]
	v_pk_add_f32 v[192:193], v[22:23], v[26:27] neg_lo:[0,1] neg_hi:[0,1]
	v_pk_add_f32 v[20:21], v[28:29], v[190:191]
	v_pk_add_f32 v[24:25], v[28:29], v[190:191] neg_lo:[0,1] neg_hi:[0,1]
	v_pk_add_f32 v[22:23], v[188:189], v[192:193] op_sel:[0,1] op_sel_hi:[1,0] neg_lo:[0,1]
	v_pk_add_f32 v[26:27], v[188:189], v[192:193] op_sel:[0,1] op_sel_hi:[1,0] neg_hi:[0,1]
	s_nop 0
	ds_write_b128 v19, v[20:23]
	ds_write_b128 v19, v[24:27] offset:16
	v_add_u32_e32 v230, 0x200, v5
	v_mov_b32_e32 v5, v230
	s_nop 0
	s_mov_b64 s[84:85], exec
